# MLA: rolling counted-lgkmcnt LDS fragment reads in S/PV; waves 4-7 take the per-tile barrier before PV (half-tile stagger), 3-slot LDS ring
# speedup vs baseline: 1.0290x; 1.0097x over previous
; template <int DQK, int W1, int DV, int VW, int MODE> ...
;     ...
;       float mx = s[0][0];
; #pragma unroll
;       for (int i = 1; i < 16; ++i) mx = fmaxf(mx, s[0][i]);
; #pragma unroll
;       for (int i = 0; i < 16; ++i) mx = fmaxf(mx, s[1][i]);
;       mx = xhalf_max(mx);
;       if (MODE == 0) {
;         if (t == 0) {
;           m = mx;
;           s[0] = s[0] - mx; s[1] = s[1] - mx; negm = negm - mx;
;         } else if (__any(mx > 8.0f)) {
;           const float d = fmaxf(mx, 0.f), alpha = __builtin_amdgcn_exp2f(-d);
;           m += d; l *= alpha;
;           s[0] = s[0] - d; s[1] = s[1] - d; negm = negm - d;
; #pragma unroll
;           for (int cb = 0; cb < NCB; ++cb)
; #pragma unroll
;             for (int r = 0; r < 16; ++r) o[cb][r] *= alpha;
;         }
;       } else if (__any(mx - m > 8.0f)) {
;         const float mnew = fmaxf(m, mx), alpha = __builtin_amdgcn_exp2f(m - mnew);
;         m = mnew; l *= alpha;
; #pragma unroll
;         for (int cb = 0; cb < NCB; ++cb)
; #pragma unroll
;           for (int r = 0; r < 16; ++r) o[cb][r] *= alpha;
;       }
;       {
;         f32x16 e0 = s[0], e1 = s[1];
;         if (MODE != 0) { const float nm = -m; e0 = e0 + nm; e1 = e1 + nm; }
; #pragma unroll
;         for (int i = 0; i < 16; ++i) { e0[i] = __builtin_amdgcn_exp2f(e0[i]); e1[i] = __builtin_amdgcn_exp2f(e1[i]); }
;         s[0] = e0; s[1] = e1;
;         const f32x16 sm = e0 + e1;
;         typedef __attribute__((ext_vector_type(8))) float f32x8;
;         const f32x8 h8 = sm.lo + sm.hi;
;         const f32x4 h4 = h8.lo + h8.hi;
;         const f32x2 h2 = h4.lo + h4.hi;
;         l += h2[0] + h2[1];
;       }
;       bf16x8 pb[2][2];
; #pragma unroll
;       for (int n = 0; n < 2; ++n)
; #pragma unroll
;         for (int s2 = 0; s2 < 2; ++s2) {
;           u32x4 pw = {pk2(s[n][8 * s2 + 0], s[n][8 * s2 + 1]), pk2(s[n][8 * s2 + 2], s[n][8 * s2 + 3]),
;                       pk2(s[n][8 * s2 + 4], s[n][8 * s2 + 5]), pk2(s[n][8 * s2 + 6], s[n][8 * s2 + 7])};
;           pb[n][s2] = __builtin_bit_cast(bf16x8, pw);
;         }
;       pv_block<0>(o[0], bufa + vlane, pb);
;       if constexpr (NCB > 1) pv_block<1>(o[1], bufa + vlane, pb);
;       if constexpr (NCB > 2) pv_block<2>(o[2], bufa + vlane, pb);
;       if constexpr (NCB > 3) pv_block<3>(o[3], bufa + vlane, pb);
.LBB0_1391:
	v_max_f32_e32 v34, v3, v3
	v_max_f32_e32 v35, v2, v2
	v_max_f32_e32 v34, v35, v34
	v_max3_f32 v34, v34, v4, v5
	v_max3_f32 v34, v34, v6, v7
	v_max3_f32 v34, v34, v8, v9
	v_max3_f32 v34, v34, v10, v11
	v_max3_f32 v34, v34, v12, v13
	v_max3_f32 v34, v34, v14, v15
	v_max3_f32 v34, v34, v16, v17
	s_nop 0
	v_max3_f32 v34, v34, v18, v19
	v_max3_f32 v34, v34, v20, v21
	v_max3_f32 v34, v34, v22, v23
	v_max3_f32 v34, v34, v24, v25
	v_max3_f32 v34, v34, v26, v27
	v_max3_f32 v34, v34, v28, v29
	v_max3_f32 v34, v34, v30, v31
	v_max3_f32 v34, v34, v32, v33
	v_mov_b32_e32 v35, v34
	s_nop 1
	v_permlane32_swap_b32_e32 v34, v35
	v_max_f32_e32 v35, v35, v35
	v_max_f32_e32 v34, v34, v34
	v_max_f32_e32 v34, v34, v35
	v_sub_f32_e32 v17, v17, v34
	v_sub_f32_e32 v16, v16, v34
	v_sub_f32_e32 v15, v15, v34
	v_sub_f32_e32 v14, v14, v34
	v_sub_f32_e32 v35, v13, v34
	v_sub_f32_e32 v36, v12, v34
	v_sub_f32_e32 v37, v11, v34
	v_sub_f32_e32 v38, v10, v34
	v_sub_f32_e32 v13, v9, v34
	v_sub_f32_e32 v12, v8, v34
	v_sub_f32_e32 v11, v7, v34
	v_sub_f32_e32 v10, v6, v34
	v_sub_f32_e32 v7, v5, v34
	v_sub_f32_e32 v6, v4, v34
	v_sub_f32_e32 v3, v3, v34
	v_sub_f32_e32 v2, v2, v34
	v_sub_f32_e32 v39, v33, v34
	v_sub_f32_e32 v40, v32, v34
	v_sub_f32_e32 v33, v31, v34
	v_sub_f32_e32 v31, v30, v34
	v_sub_f32_e32 v29, v29, v34
	v_sub_f32_e32 v28, v28, v34
	v_sub_f32_e32 v27, v27, v34
	v_sub_f32_e32 v26, v26, v34
	v_sub_f32_e32 v25, v25, v34
	v_sub_f32_e32 v24, v24, v34
	v_sub_f32_e32 v23, v23, v34
	v_sub_f32_e32 v22, v22, v34
	v_sub_f32_e32 v9, v21, v34
	v_sub_f32_e32 v8, v20, v34
	v_sub_f32_e32 v5, v19, v34
	v_sub_f32_e32 v4, v18, v34
	v_sub_f32_e32 v80, 0, v34
	v_exp_f32_e32 v2, v2
	v_exp_f32_e32 v4, v4
	v_exp_f32_e32 v3, v3
	v_exp_f32_e32 v5, v5
	v_exp_f32_e32 v6, v6
	v_exp_f32_e32 v8, v8
	v_exp_f32_e32 v7, v7
	v_exp_f32_e32 v9, v9
	v_exp_f32_e32 v10, v10
	v_exp_f32_e32 v18, v22
	v_exp_f32_e32 v11, v11
	v_exp_f32_e32 v19, v23
	v_exp_f32_e32 v12, v12
	v_exp_f32_e32 v20, v24
	v_exp_f32_e32 v13, v13
	v_exp_f32_e32 v21, v25
	v_exp_f32_e32 v22, v38
	v_exp_f32_e32 v24, v26
	v_exp_f32_e32 v23, v37
	v_exp_f32_e32 v25, v27
	v_exp_f32_e32 v26, v36
	v_exp_f32_e32 v28, v28
	v_exp_f32_e32 v27, v35
	v_exp_f32_e32 v29, v29
	v_exp_f32_e32 v30, v14
	v_exp_f32_e32 v32, v31
	v_exp_f32_e32 v31, v15
	v_exp_f32_e32 v33, v33
	v_exp_f32_e32 v34, v16
	v_exp_f32_e32 v36, v40
	v_exp_f32_e32 v35, v17
	v_exp_f32_e32 v37, v39
	v_pk_add_f32 v[14:15], v[26:27], v[28:29]
	v_pk_add_f32 v[16:17], v[6:7], v[8:9]
	v_pk_add_f32 v[40:41], v[12:13], v[20:21]
	v_pk_add_f32 v[38:39], v[34:35], v[36:37]
	v_pk_add_f32 v[42:43], v[22:23], v[24:25]
	v_pk_add_f32 v[44:45], v[2:3], v[4:5]
	v_pk_add_f32 v[46:47], v[30:31], v[32:33]
	v_pk_add_f32 v[48:49], v[10:11], v[18:19]
	v_pk_add_f32 v[42:43], v[44:45], v[42:43]
	v_pk_add_f32 v[46:47], v[48:49], v[46:47]
	v_pk_add_f32 v[38:39], v[40:41], v[38:39]
	v_pk_add_f32 v[14:15], v[16:17], v[14:15]
	v_pk_add_f32 v[16:17], v[42:43], v[46:47]
	v_pk_add_f32 v[14:15], v[14:15], v[38:39]
	s_cmp_lg_u32 0, -1
	v_pk_add_f32 v[14:15], v[16:17], v[14:15]
	v_cvt_pk_bf16_f32 v16, v10, v11
	v_add_f32_e32 v38, v14, v15
	v_cvt_pk_bf16_f32 v14, v2, v3
	v_cvt_pk_bf16_f32 v15, v6, v7
	v_cvt_pk_bf16_f32 v17, v12, v13
	s_cselect_b32 s0, 0, 0
	v_cvt_pk_bf16_f32 v10, v22, v23
	v_cvt_pk_bf16_f32 v11, v26, v27
	v_cvt_pk_bf16_f32 v12, v30, v31
	v_cvt_pk_bf16_f32 v6, v4, v5
	v_cvt_pk_bf16_f32 v7, v8, v9
	v_cvt_pk_bf16_f32 v8, v18, v19
	v_cvt_pk_bf16_f32 v9, v20, v21
	v_cvt_pk_bf16_f32 v2, v24, v25
	v_cvt_pk_bf16_f32 v3, v28, v29
	v_cvt_pk_bf16_f32 v4, v32, v33
	s_cmp_lt_u32 s26, 0x1000
	s_cbranch_scc1 .Lmla_pv0
	s_waitcnt vmcnt(0)
	s_barrier
.Lmla_pv0:
	v_add_u32_e32 v108, s0, v187
	ds_read_b64_tr_b16 v[30:31], v108 offset:0
	ds_read_b64_tr_b16 v[32:33], v108 offset:0x200
	ds_read_b64_tr_b16 v[26:27], v108 offset:0x400
	ds_read_b64_tr_b16 v[28:29], v108 offset:0x600
	ds_read_b64_tr_b16 v[22:23], v108 offset:0x800
	ds_read_b64_tr_b16 v[24:25], v108 offset:0xa00
	ds_read_b64_tr_b16 v[18:19], v108 offset:0xc00
	ds_read_b64_tr_b16 v[20:21], v108 offset:0xe00
	s_waitcnt lgkmcnt(0)
	v_cvt_pk_bf16_f32 v13, v34, v35
	v_mfma_f32_32x32x16_bf16 v[64:79], v[30:33], v[14:17], 0
	v_cvt_pk_bf16_f32 v5, v36, v37
	v_add_f32_e32 v236, 0, v38
	v_mov_b32_e32 v81, v80
	v_mov_b32_e32 v82, v80
	v_mov_b32_e32 v83, v80
	v_mov_b32_e32 v84, v80
	v_mov_b32_e32 v85, v80
	v_mfma_f32_32x32x16_bf16 v[64:79], v[26:29], v[10:13], v[64:79]
	v_mov_b32_e32 v86, v80
	v_mov_b32_e32 v87, v80
	v_mov_b32_e32 v88, v80
	v_mov_b32_e32 v89, v80
	v_mov_b32_e32 v90, v80
	v_mov_b32_e32 v91, v80
	v_mov_b32_e32 v92, v80
	v_mfma_f32_32x32x16_bf16 v[64:79], v[22:25], v[6:9], v[64:79]
	v_mov_b32_e32 v93, v80
	v_mov_b32_e32 v94, v80
	v_mov_b32_e32 v95, v80
	s_mov_b64 s[0:1], 0
	v_mfma_f32_32x32x16_bf16 v[64:79], v[18:21], v[2:5], v[64:79]
	ds_read_b64_tr_b16 v[30:31], v108 offset:0x1000
	ds_read_b64_tr_b16 v[32:33], v108 offset:0x1200
	ds_read_b64_tr_b16 v[26:27], v108 offset:0x1400
	ds_read_b64_tr_b16 v[28:29], v108 offset:0x1600
	ds_read_b64_tr_b16 v[22:23], v108 offset:0x1800
	ds_read_b64_tr_b16 v[24:25], v108 offset:0x1a00
	ds_read_b64_tr_b16 v[18:19], v108 offset:0x1c00
	ds_read_b64_tr_b16 v[20:21], v108 offset:0x1e00
	s_waitcnt lgkmcnt(0)
	s_nop 0
	v_mfma_f32_32x32x16_bf16 v[48:63], v[30:33], v[14:17], 0
	v_mfma_f32_32x32x16_bf16 v[48:63], v[26:29], v[10:13], v[48:63]
	v_mfma_f32_32x32x16_bf16 v[48:63], v[22:25], v[6:9], v[48:63]
	v_mfma_f32_32x32x16_bf16 v[48:63], v[18:21], v[2:5], v[48:63]
	ds_read_b64_tr_b16 v[30:31], v108 offset:0x2000
	ds_read_b64_tr_b16 v[32:33], v108 offset:0x2200
	ds_read_b64_tr_b16 v[26:27], v108 offset:0x2400
	ds_read_b64_tr_b16 v[28:29], v108 offset:0x2600
	ds_read_b64_tr_b16 v[22:23], v108 offset:0x2800
	ds_read_b64_tr_b16 v[24:25], v108 offset:0x2a00
	ds_read_b64_tr_b16 v[18:19], v108 offset:0x2c00
	ds_read_b64_tr_b16 v[20:21], v108 offset:0x2e00
	s_waitcnt lgkmcnt(0)
	s_nop 0
	v_mfma_f32_32x32x16_bf16 v[32:47], v[30:33], v[14:17], 0
	v_mfma_f32_32x32x16_bf16 v[32:47], v[26:29], v[10:13], v[32:47]
	v_mfma_f32_32x32x16_bf16 v[32:47], v[22:25], v[6:9], v[32:47]
	v_mfma_f32_32x32x16_bf16 v[32:47], v[18:21], v[2:5], v[32:47]
	ds_read_b64_tr_b16 v[18:19], v108 offset:0x3000
	ds_read_b64_tr_b16 v[20:21], v108 offset:0x3200
	ds_read_b64_tr_b16 v[104:105], v108 offset:0x3400
	ds_read_b64_tr_b16 v[106:107], v108 offset:0x3600
	ds_read_b64_tr_b16 v[100:101], v108 offset:0x3800
	ds_read_b64_tr_b16 v[102:103], v108 offset:0x3a00
	ds_read_b64_tr_b16 v[96:97], v108 offset:0x3c00
	ds_read_b64_tr_b16 v[98:99], v108 offset:0x3e00
	s_waitcnt lgkmcnt(0)
	s_nop 0
	v_mfma_f32_32x32x16_bf16 v[16:31], v[18:21], v[14:17], 0
	v_mfma_f32_32x32x16_bf16 v[16:31], v[104:107], v[10:13], v[16:31]
	v_mfma_f32_32x32x16_bf16 v[16:31], v[100:103], v[6:9], v[16:31]
	v_mfma_f32_32x32x16_bf16 v[16:31], v[96:99], v[2:5], v[16:31]

; template <int DQK, int W1, int DV, int VW, int MODE> ...
;     ...
;   for (int t = 0; t < ntiles; ++t) {
;     const int kb = kbase0 + t * 64;
;     const unsigned bufa = lds0 + (unsigned)((t & 1) * BUF);
;     const unsigned mw0 = mwn[0], mw1 = mwn[1];
;     if (t + 1 < ntiles) stage_tile(kb + 64, (t + 1) & 1);
;     ...
;     asm volatile("s_waitcnt vmcnt(0)" ::: "memory");
;     __syncthreads();
.LBB0_1394:
	s_sub_i32 s29, 0, s29
	s_lshl_b32 s1, s28, 2
	s_or_b32 s0, s54, 31
	s_add_i32 s1, s1, 4
	s_lshl_b32 s28, s29, 2
	s_movk_i32 s29, 0xffe1
	s_movk_i32 s69, 0x7f
	s_mov_b32 s100, 0xa400
	s_cmp_ge_u32 s26, 0x1000
	s_cbranch_scc1 .Lmla_b0
	s_waitcnt vmcnt(0) lgkmcnt(0)
	s_barrier

; template <int DQK, int W1, int DV, int VW, int MODE> ...
;     ...
;       {
;         f32x16 e0 = s[0], e1 = s[1];
;         if (MODE != 0) { const float nm = -m; e0 = e0 + nm; e1 = e1 + nm; }
; #pragma unroll
;         for (int i = 0; i < 16; ++i) { e0[i] = __builtin_amdgcn_exp2f(e0[i]); e1[i] = __builtin_amdgcn_exp2f(e1[i]); }
;         s[0] = e0; s[1] = e1;
;         const f32x16 sm = e0 + e1;
;         typedef __attribute__((ext_vector_type(8))) float f32x8;
;         const f32x8 h8 = sm.lo + sm.hi;
;         const f32x4 h4 = h8.lo + h8.hi;
;         const f32x2 h2 = h4.lo + h4.hi;
;         l += h2[0] + h2[1];
;       }
;       bf16x8 pb[2][2];
; #pragma unroll
;       for (int n = 0; n < 2; ++n)
; #pragma unroll
;         for (int s2 = 0; s2 < 2; ++s2) {
;           u32x4 pw = {pk2(s[n][8 * s2 + 0], s[n][8 * s2 + 1]), pk2(s[n][8 * s2 + 2], s[n][8 * s2 + 3]),
;                       pk2(s[n][8 * s2 + 4], s[n][8 * s2 + 5]), pk2(s[n][8 * s2 + 6], s[n][8 * s2 + 7])};
;           pb[n][s2] = __builtin_bit_cast(bf16x8, pw);
;         }
;       pv_block<0>(o[0], bufa + vlane, pb);
;       if constexpr (NCB > 1) pv_block<1>(o[1], bufa + vlane, pb);
;       if constexpr (NCB > 2) pv_block<2>(o[2], bufa + vlane, pb);
;       if constexpr (NCB > 3) pv_block<3>(o[3], bufa + vlane, pb);
.LBB0_1395:
	v_exp_f32_e32 v2, v96
	v_exp_f32_e32 v4, v112
	v_exp_f32_e32 v3, v97
	v_exp_f32_e32 v5, v113
	v_exp_f32_e32 v6, v98
	v_exp_f32_e32 v8, v114
	v_exp_f32_e32 v7, v99
	v_exp_f32_e32 v9, v115
	v_exp_f32_e32 v10, v100
	v_exp_f32_e32 v14, v116
	v_exp_f32_e32 v11, v101
	v_exp_f32_e32 v15, v117
	v_exp_f32_e32 v12, v102
	v_exp_f32_e32 v100, v118
	v_exp_f32_e32 v13, v103
	v_exp_f32_e32 v101, v119
	v_exp_f32_e32 v102, v104
	v_exp_f32_e32 v104, v120
	v_exp_f32_e32 v103, v105
	v_exp_f32_e32 v105, v121
	v_exp_f32_e32 v106, v106
	v_exp_f32_e32 v112, v122
	v_exp_f32_e32 v107, v107
	v_exp_f32_e32 v113, v123
	v_exp_f32_e32 v108, v108
	v_exp_f32_e32 v114, v124
	v_exp_f32_e32 v109, v109
	v_exp_f32_e32 v115, v125
	v_exp_f32_e32 v110, v110
	v_exp_f32_e32 v116, v126
	v_exp_f32_e32 v111, v111
	v_exp_f32_e32 v117, v127
	v_pk_add_f32 v[96:97], v[106:107], v[112:113]
	v_pk_add_f32 v[98:99], v[6:7], v[8:9]
	v_pk_add_f32 v[120:121], v[12:13], v[100:101]
	v_pk_add_f32 v[118:119], v[110:111], v[116:117]
	v_pk_add_f32 v[122:123], v[102:103], v[104:105]
	v_pk_add_f32 v[124:125], v[2:3], v[4:5]
	v_pk_add_f32 v[126:127], v[108:109], v[114:115]
	v_pk_add_f32 v[208:209], v[10:11], v[14:15]
	v_pk_add_f32 v[122:123], v[124:125], v[122:123]
	v_pk_add_f32 v[126:127], v[208:209], v[126:127]
	v_pk_add_f32 v[118:119], v[120:121], v[118:119]
	v_pk_add_f32 v[96:97], v[98:99], v[96:97]
	v_pk_add_f32 v[98:99], v[122:123], v[126:127]
	v_pk_add_f32 v[96:97], v[96:97], v[118:119]
	s_nop 0
	v_pk_add_f32 v[96:97], v[98:99], v[96:97]
	v_cvt_pk_bf16_f32 v98, v10, v11
	v_add_f32_e32 v118, v96, v97
	v_cvt_pk_bf16_f32 v96, v2, v3
	v_cvt_pk_bf16_f32 v97, v6, v7
	v_cvt_pk_bf16_f32 v99, v12, v13
	v_cvt_pk_bf16_f32 v10, v102, v103
	v_cvt_pk_bf16_f32 v11, v106, v107
	v_cvt_pk_bf16_f32 v12, v108, v109
	v_cvt_pk_bf16_f32 v13, v110, v111
	v_cvt_pk_bf16_f32 v6, v4, v5
	v_cvt_pk_bf16_f32 v7, v8, v9
	v_cvt_pk_bf16_f32 v8, v14, v15
	v_cvt_pk_bf16_f32 v9, v100, v101
	v_cvt_pk_bf16_f32 v2, v104, v105
	v_cvt_pk_bf16_f32 v3, v112, v113
	v_cvt_pk_bf16_f32 v4, v114, v115
	s_cmp_lt_u32 s26, 0x1000
	s_cbranch_scc1 .Lmla_pv
	s_waitcnt vmcnt(0)
	s_barrier
.Lmla_pv:
	v_add_u32_e32 v14, s70, v187
	ds_read_b64_tr_b16 v[112:113], v14
	ds_read_b64_tr_b16 v[114:115], v14 offset:512
	ds_read_b64_tr_b16 v[108:109], v14 offset:1024
	ds_read_b64_tr_b16 v[110:111], v14 offset:1536
	ds_read_b64_tr_b16 v[104:105], v14 offset:2048
	ds_read_b64_tr_b16 v[106:107], v14 offset:2560
	ds_read_b64_tr_b16 v[100:101], v14 offset:3072
	ds_read_b64_tr_b16 v[102:103], v14 offset:3584
	v_cvt_pk_bf16_f32 v5, v116, v117
	v_add_f32_e32 v236, v236, v118
	s_waitcnt lgkmcnt(6)
	v_mfma_f32_32x32x16_bf16 v[64:79], v[112:115], v[96:99], v[64:79]
	ds_read_b64_tr_b16 v[112:113], v14 offset:4096
	ds_read_b64_tr_b16 v[114:115], v14 offset:4608
	s_waitcnt lgkmcnt(6)
	v_mfma_f32_32x32x16_bf16 v[64:79], v[108:111], v[10:13], v[64:79]
	ds_read_b64_tr_b16 v[108:109], v14 offset:5120
	ds_read_b64_tr_b16 v[110:111], v14 offset:5632
	s_waitcnt lgkmcnt(6)
	v_mfma_f32_32x32x16_bf16 v[64:79], v[104:107], v[6:9], v[64:79]
	ds_read_b64_tr_b16 v[104:105], v14 offset:6144
	ds_read_b64_tr_b16 v[106:107], v14 offset:6656
	s_waitcnt lgkmcnt(6)
	v_mfma_f32_32x32x16_bf16 v[64:79], v[100:103], v[2:5], v[64:79]
	ds_read_b64_tr_b16 v[100:101], v14 offset:7168
	ds_read_b64_tr_b16 v[102:103], v14 offset:7680
	s_waitcnt lgkmcnt(6)
	v_mfma_f32_32x32x16_bf16 v[48:63], v[112:115], v[96:99], v[48:63]
	ds_read_b64_tr_b16 v[112:113], v14 offset:8192
	ds_read_b64_tr_b16 v[114:115], v14 offset:8704
	s_waitcnt lgkmcnt(6)
	v_mfma_f32_32x32x16_bf16 v[48:63], v[108:111], v[10:13], v[48:63]
	ds_read_b64_tr_b16 v[108:109], v14 offset:9216
	ds_read_b64_tr_b16 v[110:111], v14 offset:9728
	s_waitcnt lgkmcnt(6)
	v_mfma_f32_32x32x16_bf16 v[48:63], v[104:107], v[6:9], v[48:63]
	ds_read_b64_tr_b16 v[104:105], v14 offset:10240
	ds_read_b64_tr_b16 v[106:107], v14 offset:10752
	s_waitcnt lgkmcnt(6)
	v_mfma_f32_32x32x16_bf16 v[48:63], v[100:103], v[2:5], v[48:63]
	ds_read_b64_tr_b16 v[100:101], v14 offset:11264
	ds_read_b64_tr_b16 v[102:103], v14 offset:11776
	s_waitcnt lgkmcnt(6)
	v_mfma_f32_32x32x16_bf16 v[32:47], v[112:115], v[96:99], v[32:47]
	ds_read_b64_tr_b16 v[112:113], v14 offset:12288
	ds_read_b64_tr_b16 v[114:115], v14 offset:12800
	s_waitcnt lgkmcnt(6)
	v_mfma_f32_32x32x16_bf16 v[32:47], v[108:111], v[10:13], v[32:47]
	ds_read_b64_tr_b16 v[108:109], v14 offset:13312
	ds_read_b64_tr_b16 v[110:111], v14 offset:13824
	s_waitcnt lgkmcnt(6)
	v_mfma_f32_32x32x16_bf16 v[32:47], v[104:107], v[6:9], v[32:47]
	ds_read_b64_tr_b16 v[104:105], v14 offset:14336
	ds_read_b64_tr_b16 v[106:107], v14 offset:14848
	s_waitcnt lgkmcnt(6)
	v_mfma_f32_32x32x16_bf16 v[32:47], v[100:103], v[2:5], v[32:47]
	ds_read_b64_tr_b16 v[100:101], v14 offset:15360
	ds_read_b64_tr_b16 v[102:103], v14 offset:15872
	s_waitcnt lgkmcnt(6)
	v_mfma_f32_32x32x16_bf16 v[16:31], v[112:115], v[96:99], v[16:31]
	s_waitcnt lgkmcnt(4)
	v_mfma_f32_32x32x16_bf16 v[16:31], v[108:111], v[10:13], v[16:31]
	s_waitcnt lgkmcnt(2)
	v_mfma_f32_32x32x16_bf16 v[16:31], v[104:107], v[6:9], v[16:31]
	s_waitcnt lgkmcnt(0)
	v_mfma_f32_32x32x16_bf16 v[16:31], v[100:103], v[2:5], v[16:31]
.LBB0_1396:
	s_cmp_ge_u32 s26, 0x1000
	s_cbranch_scc1 .Lmla_nobar

; template <int DQK, int W1, int DV, int VW, int MODE> ...
;     ...
;   for (int t = 0; t < ntiles; ++t) {
;     const int kb = kbase0 + t * 64;
;     const unsigned bufa = lds0 + (unsigned)((t & 1) * BUF);
;     const unsigned mw0 = mwn[0], mw1 = mwn[1];
;     if (t + 1 < ntiles) stage_tile(kb + 64, (t + 1) & 1);
;     ...
;     asm volatile("s_waitcnt vmcnt(0)" ::: "memory");
;     __syncthreads();
;   }
.Lmla_nobar:
	s_add_u32 s100, s100, 0xa400
	s_cmp_eq_u32 s100, 0x1ec00
	s_cselect_b32 s100, 0, s100
	s_add_i32 s29, s29, 1
	s_add_i32 s69, s69, 64
	s_cmp_eq_u32 s28, s29
	s_waitcnt lgkmcnt(0)
	s_cbranch_scc1 .Lmla_exit
.LBB0_1397:
	s_add_i32 s30, s29, 33
	s_cmp_ge_i32 s30, s1
	s_cbranch_scc1 .LBB0_1405
	s_add_u32 s30, s100, 0xa400
	s_cmp_eq_u32 s30, 0x1ec00
	s_cselect_b32 s30, 0, s30
	s_and_b64 vcc, exec, s[8:9]
	s_cbranch_vccz .LBB0_1410
	s_and_b64 vcc, exec, s[10:11]
	s_cbranch_vccz .LBB0_1411

; DI int crow(int reg, int hi) { return (reg & 3) + 8 * (reg >> 2) + 4 * hi; }
; template <int DQK, int W1, int DV, int VW, int MODE> ...
;     ...
;     if (!(MODE == 0 && kb > tq0 + 31)) {
;       f32x16 s[2];
;       s[0] = s_block<KSTR, ND, 0>(bufa + klane, qf, negm);
;       s[1] = s_block<KSTR, ND, 1>(bufa + klane, qf, negm);
;       if (MODE == 0) {
;         if (__builtin_amdgcn_readfirstlane((int)(kb + 63 > tq0))) {
; #pragma unroll
;           for (int n = 0; n < 2; ++n)
; #pragma unroll
;             for (int i = 0; i < 16; ++i) { const int key = kb + 32 * n + crow(i, hi); if (key > tq) s[n][i] = NEGV; }
;         }
.LBB0_1405:
	s_sub_i32 s30, s69, 63
	s_cmp_gt_i32 s30, s0
	s_cbranch_scc1 .Lmla_dobar
	s_mov_b32 s31, 0
	s_mov_b32 s70, s100
	v_add_u32_e32 v14, s70, v189
	ds_read_b128 v[2:5], v14
	ds_read_b128 v[6:9], v14 offset:32
	ds_read_b128 v[10:13], v14 offset:64
	ds_read_b128 v[112:115], v14 offset:96
	s_waitcnt lgkmcnt(3)
	v_mfma_f32_32x32x16_bf16 v[96:111], v[2:5], v[128:131], v[80:95]
	ds_read_b128 v[2:5], v14 offset:128
	s_waitcnt lgkmcnt(3)
	v_mfma_f32_32x32x16_bf16 v[96:111], v[6:9], v[132:135], v[96:111]
	ds_read_b128 v[6:9], v14 offset:160
	s_waitcnt lgkmcnt(3)
	v_mfma_f32_32x32x16_bf16 v[96:111], v[10:13], v[136:139], v[96:111]
	ds_read_b128 v[10:13], v14 offset:192
	s_waitcnt lgkmcnt(3)
	v_mfma_f32_32x32x16_bf16 v[96:111], v[112:115], v[140:143], v[96:111]
	ds_read_b128 v[112:115], v14 offset:224
	s_waitcnt lgkmcnt(3)
	v_mfma_f32_32x32x16_bf16 v[96:111], v[2:5], v[144:147], v[96:111]
	ds_read_b128 v[2:5], v14 offset:256
	s_waitcnt lgkmcnt(3)
	v_mfma_f32_32x32x16_bf16 v[96:111], v[6:9], v[148:151], v[96:111]
	ds_read_b128 v[6:9], v14 offset:288
	s_waitcnt lgkmcnt(3)
	v_mfma_f32_32x32x16_bf16 v[96:111], v[10:13], v[152:155], v[96:111]
	ds_read_b128 v[10:13], v14 offset:320
	s_waitcnt lgkmcnt(3)
	v_mfma_f32_32x32x16_bf16 v[96:111], v[112:115], v[156:159], v[96:111]
	ds_read_b128 v[112:115], v14 offset:352
	s_waitcnt lgkmcnt(3)
	v_mfma_f32_32x32x16_bf16 v[96:111], v[2:5], v[160:163], v[96:111]
	ds_read_b128 v[2:5], v14 offset:12800
	s_waitcnt lgkmcnt(3)
	v_mfma_f32_32x32x16_bf16 v[96:111], v[6:9], v[164:167], v[96:111]
	ds_read_b128 v[6:9], v14 offset:12832
	s_waitcnt lgkmcnt(3)
	v_mfma_f32_32x32x16_bf16 v[96:111], v[10:13], v[168:171], v[96:111]
	ds_read_b128 v[10:13], v14 offset:12864
	s_waitcnt lgkmcnt(3)
	v_mfma_f32_32x32x16_bf16 v[96:111], v[112:115], v[172:175], v[96:111]
	ds_read_b128 v[208:211], v14 offset:12896
	s_waitcnt lgkmcnt(3)
	v_mfma_f32_32x32x16_bf16 v[112:127], v[2:5], v[128:131], v[80:95]
	ds_read_b128 v[2:5], v14 offset:12928
	s_waitcnt lgkmcnt(3)
	v_mfma_f32_32x32x16_bf16 v[112:127], v[6:9], v[132:135], v[112:127]
	ds_read_b128 v[6:9], v14 offset:12960
	s_waitcnt lgkmcnt(3)
	v_mfma_f32_32x32x16_bf16 v[112:127], v[10:13], v[136:139], v[112:127]
	ds_read_b128 v[10:13], v14 offset:12992
	s_waitcnt lgkmcnt(3)
	v_mfma_f32_32x32x16_bf16 v[112:127], v[208:211], v[140:143], v[112:127]
	ds_read_b128 v[208:211], v14 offset:13024
	s_waitcnt lgkmcnt(3)
	v_mfma_f32_32x32x16_bf16 v[112:127], v[2:5], v[144:147], v[112:127]
	ds_read_b128 v[2:5], v14 offset:13056
	s_waitcnt lgkmcnt(3)
	v_mfma_f32_32x32x16_bf16 v[112:127], v[6:9], v[148:151], v[112:127]
	ds_read_b128 v[6:9], v14 offset:13088
	s_waitcnt lgkmcnt(3)
	v_mfma_f32_32x32x16_bf16 v[112:127], v[10:13], v[152:155], v[112:127]
	ds_read_b128 v[10:13], v14 offset:13120
	s_waitcnt lgkmcnt(3)
	v_mfma_f32_32x32x16_bf16 v[112:127], v[208:211], v[156:159], v[112:127]
	ds_read_b128 v[208:211], v14 offset:13152
	s_waitcnt lgkmcnt(3)
	v_mfma_f32_32x32x16_bf16 v[112:127], v[2:5], v[160:163], v[112:127]
	s_waitcnt lgkmcnt(2)
	v_mfma_f32_32x32x16_bf16 v[112:127], v[6:9], v[164:167], v[112:127]
	s_waitcnt lgkmcnt(1)
	v_mfma_f32_32x32x16_bf16 v[112:127], v[10:13], v[168:171], v[112:127]
	s_waitcnt lgkmcnt(0)
	v_mfma_f32_32x32x16_bf16 v[112:127], v[208:211], v[172:175], v[112:127]
	s_cmp_le_i32 s69, s54
	s_cbranch_scc1 .LBB0_1408
	v_add_u32_e32 v2, s69, v188
	v_subrev_u32_e32 v3, 63, v2
	v_cmp_gt_i32_e32 vcc, v3, v186
	s_nop 1
	v_cndmask_b32_e32 v4, v96, v232, vcc
	v_cmp_lt_i32_e32 vcc, v3, v186
	v_subrev_u32_e32 v3, 61, v2
	s_nop 0
	v_cndmask_b32_e32 v96, v4, v96, vcc
	v_cndmask_b32_e32 v97, v232, v97, vcc
	v_cmp_le_i32_e32 vcc, v3, v186
	v_subrev_u32_e32 v3, 60, v2
	s_nop 0
	v_cndmask_b32_e32 v98, v232, v98, vcc
	v_cmp_le_i32_e32 vcc, v3, v186
	v_subrev_u32_e32 v3, 55, v2
	s_nop 0
	v_cndmask_b32_e32 v99, v232, v99, vcc
	v_cmp_le_i32_e32 vcc, v3, v186
	v_subrev_u32_e32 v3, 54, v2
	s_nop 0
	v_cndmask_b32_e32 v100, v232, v100, vcc
	v_cmp_le_i32_e32 vcc, v3, v186
	v_subrev_u32_e32 v3, 53, v2
	s_nop 0
	v_cndmask_b32_e32 v101, v232, v101, vcc
	v_cmp_le_i32_e32 vcc, v3, v186
	v_subrev_u32_e32 v3, 52, v2
	s_nop 0
	v_cndmask_b32_e32 v102, v232, v102, vcc
	v_cmp_le_i32_e32 vcc, v3, v186
	v_subrev_u32_e32 v3, 47, v2
	s_nop 0
	v_cndmask_b32_e32 v103, v232, v103, vcc
	v_cmp_le_i32_e32 vcc, v3, v186
	v_subrev_u32_e32 v3, 46, v2
	s_nop 0
	v_cndmask_b32_e32 v104, v232, v104, vcc
	v_cmp_le_i32_e32 vcc, v3, v186
	v_subrev_u32_e32 v3, 45, v2
	s_nop 0
	v_cndmask_b32_e32 v105, v232, v105, vcc
	v_cmp_le_i32_e32 vcc, v3, v186
	v_subrev_u32_e32 v3, 44, v2
	s_nop 0
	v_cndmask_b32_e32 v106, v232, v106, vcc
	v_cmp_le_i32_e32 vcc, v3, v186
	v_subrev_u32_e32 v3, 39, v2
	s_nop 0
	v_cndmask_b32_e32 v107, v232, v107, vcc
	v_cmp_le_i32_e32 vcc, v3, v186
	v_subrev_u32_e32 v3, 38, v2
	s_nop 0
	v_cndmask_b32_e32 v108, v232, v108, vcc
	v_cmp_le_i32_e32 vcc, v3, v186
	v_subrev_u32_e32 v3, 37, v2
	s_nop 0
	v_cndmask_b32_e32 v109, v232, v109, vcc
	v_cmp_le_i32_e32 vcc, v3, v186
	v_subrev_u32_e32 v3, 36, v2
	s_nop 0
	v_cndmask_b32_e32 v110, v232, v110, vcc
	v_cmp_le_i32_e32 vcc, v3, v186
	v_subrev_u32_e32 v3, 31, v2
	s_nop 0
	v_cndmask_b32_e32 v111, v232, v111, vcc
	v_cmp_le_i32_e32 vcc, v3, v186
	v_subrev_u32_e32 v3, 30, v2
	s_nop 0
	v_cndmask_b32_e32 v112, v232, v112, vcc
	v_cmp_le_i32_e32 vcc, v3, v186
	v_subrev_u32_e32 v3, 29, v2
	s_nop 0
	v_cndmask_b32_e32 v113, v232, v113, vcc
	v_cmp_le_i32_e32 vcc, v3, v186
	v_subrev_u32_e32 v3, 28, v2
	s_nop 0
	v_cndmask_b32_e32 v114, v232, v114, vcc
	v_cmp_le_i32_e32 vcc, v3, v186
	v_subrev_u32_e32 v3, 23, v2
	s_nop 0
	v_cndmask_b32_e32 v115, v232, v115, vcc
	v_cmp_le_i32_e32 vcc, v3, v186
	v_subrev_u32_e32 v3, 22, v2
	s_nop 0
	v_cndmask_b32_e32 v116, v232, v116, vcc
	v_cmp_le_i32_e32 vcc, v3, v186
	v_subrev_u32_e32 v3, 21, v2
	s_nop 0
	v_cndmask_b32_e32 v117, v232, v117, vcc
	v_cmp_le_i32_e32 vcc, v3, v186
	v_subrev_u32_e32 v3, 20, v2
	s_nop 0
	v_cndmask_b32_e32 v118, v232, v118, vcc
	v_cmp_le_i32_e32 vcc, v3, v186
	v_add_u32_e32 v3, -15, v2
	s_nop 0
	v_cndmask_b32_e32 v119, v232, v119, vcc
	v_cmp_le_i32_e32 vcc, v3, v186
	v_add_u32_e32 v3, -14, v2
	s_nop 0
	v_cndmask_b32_e32 v120, v232, v120, vcc
	v_cmp_le_i32_e32 vcc, v3, v186
	v_add_u32_e32 v3, -13, v2
	s_nop 0
	v_cndmask_b32_e32 v121, v232, v121, vcc
	v_cmp_le_i32_e32 vcc, v3, v186
	v_add_u32_e32 v3, -12, v2
	s_nop 0
	v_cndmask_b32_e32 v122, v232, v122, vcc
	v_cmp_le_i32_e32 vcc, v3, v186
	v_add_u32_e32 v3, -7, v2
	s_nop 0
	v_cndmask_b32_e32 v123, v232, v123, vcc
	v_cmp_le_i32_e32 vcc, v3, v186
	v_add_u32_e32 v3, -6, v2
	s_nop 0
	v_cndmask_b32_e32 v124, v232, v124, vcc
	v_cmp_le_i32_e32 vcc, v3, v186
	v_add_u32_e32 v3, -5, v2
	v_add_u32_e32 v2, -4, v2
	v_cndmask_b32_e32 v125, v232, v125, vcc
	v_cmp_le_i32_e32 vcc, v3, v186
	s_nop 1
	v_cndmask_b32_e32 v126, v232, v126, vcc
	v_cmp_le_i32_e32 vcc, v2, v186
	s_nop 1
	v_cndmask_b32_e32 v127, v232, v127, vcc

; template <int DQK, int W1, int DV, int VW, int MODE> ...
;     ...
;     asm volatile("s_waitcnt vmcnt(0)" ::: "memory");
;     __syncthreads();
;   }
.Lmla_exit:
	s_barrier
	s_branch .LBB0_1238
